# attention C loop: one static s_setprio 1 for waves 4-7 (younger half) before the main loop, reset after
# baseline (speedup 1.0000x reference)
.LBB0_739:
	s_lshl_b32 s8, s56, 5
	s_add_i32 s8, s8, s55
	v_readlane_b32 s18, v254, 6
	s_or_b32 s8, s8, s54
	v_readlane_b32 s19, v254, 7
	s_and_b64 s[18:19], s[18:19], exec
	s_cselect_b32 s58, s8, s45
	s_ashr_i32 s18, s58, 6
	s_lshl_b32 s8, s58, 7
	s_ashr_i32 s19, s18, 31
	s_and_b32 s8, s8, 0x780
	s_lshl_b64 s[40:41], s[18:19], 20
	s_lshl_b64 s[42:43], s[18:19], 21
	s_add_u32 s17, s12, s42
	s_addc_u32 s18, s13, s43
	s_lshl_b32 s19, s58, 3
	s_and_b32 s57, s19, 0x180
	s_lshl_b32 s22, s57, 1
	s_add_u32 s17, s17, s22
	s_addc_u32 s19, s18, 0
	s_add_u32 s18, s17, s38
	s_addc_u32 s19, s19, s39
	s_add_u32 s17, s48, s42
	s_addc_u32 s21, s49, s43
	s_add_u32 s20, s17, s22
	s_addc_u32 s21, s21, 0
	s_add_u32 s17, s50, s42
	s_addc_u32 s23, s51, s43
	s_add_u32 s22, s17, s22
	s_addc_u32 s23, s23, 0
	v_lshl_add_u64 v[0:1], s[20:21], 0, v[216:217]
	v_lshl_add_u64 v[2:3], s[20:21], 0, v[220:221]
	v_lshl_add_u64 v[8:9], s[22:23], 0, v[216:217]
	v_lshl_add_u64 v[10:11], s[22:23], 0, v[220:221]
	v_lshl_add_u64 v[0:1], v[0:1], 0, v[218:219]
	v_lshl_add_u64 v[4:5], v[2:3], 0, v[222:223]
	v_lshl_add_u64 v[8:9], v[8:9], 0, v[218:219]
	v_lshl_add_u64 v[12:13], v[10:11], 0, v[222:223]
	global_load_dwordx4 v[0:3], v[0:1], off
	s_nop 0
	global_load_dwordx4 v[4:7], v[4:5], off
	s_nop 0
	global_load_dwordx4 v[8:11], v[8:9], off
	s_nop 0
	global_load_dwordx4 v[12:15], v[12:13], off
	v_or_b32_e32 v16, s8, v233
	v_lshlrev_b32_e32 v192, 10, v16
	v_lshl_add_u64 v[16:17], s[18:19], 0, v[192:193]
	v_mov_b32_e32 v215, v193
	v_lshl_add_u64 v[16:17], v[16:17], 0, v[214:215]
	global_load_dwordx4 v[160:163], v[16:17], off
	global_load_dwordx4 v[164:167], v[16:17], off offset:32
	global_load_dwordx4 v[168:171], v[16:17], off offset:64
	global_load_dwordx4 v[172:175], v[16:17], off offset:96
	v_lshl_add_u64 v[16:17], s[20:21], 0, v[196:197]
	v_lshl_add_u64 v[18:19], s[20:21], 0, v[198:199]
	v_lshl_add_u64 v[16:17], v[16:17], 0, v[218:219]
	v_lshl_add_u64 v[18:19], v[18:19], 0, v[222:223]
	global_load_dwordx4 v[176:179], v[16:17], off
	global_load_dwordx4 v[180:183], v[18:19], off
	v_add_u32_e32 v192, v202, v234
	v_add_u32_e32 v215, v204, v235
	v_add_u32_e32 v243, v206, v234
	v_add_u32_e32 v244, v208, v235
	s_mov_b32 s17, s16
	s_mov_b32 s18, s16
	s_mov_b32 s19, s16
	s_mov_b32 s20, s16
	s_mov_b32 s21, s16
	s_mov_b32 s22, s16
	s_mov_b32 s23, s16
	s_mov_b32 s24, s16
	s_mov_b32 s25, s16
	s_mov_b32 s26, s16
	s_mov_b32 s27, s16
	s_mov_b32 s28, s16
	s_mov_b32 s29, s16
	s_mov_b32 s30, s16
	s_mov_b32 s31, s16
	v_mov_b32_e32 v246, 0
	v_mov_b32_e32 v245, 0xf149f2ca
	s_waitcnt vmcnt(9)
	ds_write_b128 v192, v[0:3]
	s_waitcnt vmcnt(8)
	ds_write_b128 v215, v[4:7]
	s_waitcnt vmcnt(7)
	ds_write_b128 v243, v[8:11] offset:34816
	s_waitcnt vmcnt(6)
	ds_write_b128 v244, v[12:15] offset:34816
	s_waitcnt lgkmcnt(0)
	s_barrier
	ds_read_b128 v[0:3], v240
	ds_read_b128 v[4:7], v240 offset:32
	s_waitcnt vmcnt(5) lgkmcnt(1)
	v_mfma_f32_32x32x16_bf16 v[80:95], v[0:3], v[160:163], 0
	ds_read_b128 v[0:3], v240 offset:8704
	ds_read_b128 v[8:11], v240 offset:8736
	s_waitcnt lgkmcnt(1)
	v_mfma_f32_32x32x16_bf16 v[64:79], v[0:3], v[160:163], 0
	ds_read_b128 v[0:3], v240 offset:64
	s_waitcnt vmcnt(4)
	v_mfma_f32_32x32x16_bf16 v[80:95], v[4:7], v[164:167], v[80:95]
	ds_read_b128 v[4:7], v240 offset:8768
	ds_read_b128 v[16:19], v240 offset:96
	ds_read_b128 v[20:23], v240 offset:8800
	s_waitcnt vmcnt(1)
	ds_write_b128 v241, v[176:179] offset:17408
	s_waitcnt vmcnt(0)
	ds_write_b128 v242, v[180:183] offset:17408
	s_waitcnt lgkmcnt(0)
	s_barrier
	v_mfma_f32_32x32x16_bf16 v[64:79], v[8:11], v[164:167], v[64:79]
	v_mfma_f32_32x32x16_bf16 v[80:95], v[0:3], v[168:171], v[80:95]
	v_mfma_f32_32x32x16_bf16 v[64:79], v[4:7], v[168:171], v[64:79]
	v_mov_b64_e32 v[0:1], s[16:17]
	v_mov_b64_e32 v[2:3], s[18:19]
	v_mov_b64_e32 v[4:5], s[20:21]
	v_mov_b64_e32 v[6:7], s[22:23]
	v_mov_b64_e32 v[8:9], s[24:25]
	v_mov_b64_e32 v[10:11], s[26:27]
	v_mov_b64_e32 v[12:13], s[28:29]
	v_mfma_f32_32x32x16_bf16 v[80:95], v[16:19], v[172:175], v[80:95]
	v_mov_b64_e32 v[14:15], s[30:31]
	s_lshl_b32 s17, s58, 4
	s_and_b32 s17, s17, 0x300
	s_or_b32 s42, s42, s17
	v_mov_b64_e32 v[46:47], v[14:15]
	v_mov_b64_e32 v[62:63], v[14:15]
	v_lshl_add_u64 v[224:225], v[210:211], 0, s[42:43]
	v_mfma_f32_32x32x16_bf16 v[64:79], v[20:23], v[172:175], v[64:79]
	v_mov_b64_e32 v[30:31], v[14:15]
	v_lshl_add_u64 v[226:227], v[212:213], 0, s[42:43]
	s_mov_b64 s[18:19], 0
	v_mov_b64_e32 v[28:29], v[12:13]
	v_mov_b64_e32 v[26:27], v[10:11]
	v_mov_b64_e32 v[24:25], v[8:9]
	v_mov_b64_e32 v[22:23], v[6:7]
	v_mov_b64_e32 v[20:21], v[4:5]
	v_mov_b64_e32 v[18:19], v[2:3]
	v_mov_b64_e32 v[16:17], v[0:1]
	v_mov_b64_e32 v[44:45], v[12:13]
	v_mov_b64_e32 v[42:43], v[10:11]
	v_mov_b64_e32 v[40:41], v[8:9]
	v_mov_b64_e32 v[38:39], v[6:7]
	v_mov_b64_e32 v[36:37], v[4:5]
	v_mov_b64_e32 v[34:35], v[2:3]
	v_mov_b64_e32 v[32:33], v[0:1]
	v_mov_b64_e32 v[60:61], v[12:13]
	v_mov_b64_e32 v[58:59], v[10:11]
	v_mov_b64_e32 v[56:57], v[8:9]
	v_mov_b64_e32 v[54:55], v[6:7]
	v_mov_b64_e32 v[52:53], v[4:5]
	v_mov_b64_e32 v[50:51], v[2:3]
	v_mov_b64_e32 v[48:49], v[0:1]
	v_readfirstlane_b32 s98, v226
	v_readfirstlane_b32 s99, v227
	s_nop 3
	v_subrev_u32_e32 v247, s98, v226
	v_add_u32_e32 v252, 0x8000, v247
	v_add_u32_e32 v253, 0x10000, v247
	v_add_u32_e32 v245, 0x18000, v247
	s_add_u32 s100, s98, 0xbf10000
	s_addc_u32 s101, s99, 0
	s_add_u32 s98, s98, 0xaf20000
	s_addc_u32 s99, s99, 0
	s_mov_b32 s17, 0
	s_cmp_lg_u64 s[14:15], 0
	s_cbranch_scc0 .Lprio_skip_0
	s_setprio 1
.Lprio_skip_0:
	v_mov_b32_e32 v140, 0
	v_mov_b32_e32 v141, 0
	v_mov_b32_e32 v142, 0
	v_mov_b32_e32 v143, 0
	v_mov_b32_e32 v156, 0
	v_mov_b32_e32 v157, 0
	v_mov_b32_e32 v158, 0
	v_mov_b32_e32 v159, 0
	v_mov_b32_e32 v228, 0
	v_mov_b32_e32 v229, 0
	v_mov_b32_e32 v230, 0
	v_mov_b32_e32 v231, 0

.LBB0_759:
	s_setprio 0
	v_mfma_f32_32x32x16_bf16 v[16:31], v[156:159], v[140:143], v[16:31]
	v_mfma_f32_32x32x16_bf16 v[0:15], v[228:231], v[140:143], v[0:15]
	v_mov_b32_e32 v64, v246
	s_nop 1
	v_permlane32_swap_b32_e32 v246, v64
	v_add_f32_e32 v64, v246, v64
	v_div_scale_f32 v65, s[18:19], v64, v64, 1.0
	v_rcp_f32_e32 v66, v65
	s_nop 0
	v_fma_f32 v67, -v65, v66, 1.0
	v_fmac_f32_e32 v66, v67, v66
	v_div_scale_f32 v67, vcc, 1.0, v64, 1.0
	v_mul_f32_e32 v68, v67, v66
	v_fma_f32 v69, -v65, v68, v67
	v_fmac_f32_e32 v68, v69, v66
	v_fma_f32 v65, -v65, v68, v67
	v_div_fmas_f32 v65, v65, v66, v68
	s_andn2_b64 vcc, exec, s[14:15]
	v_div_fixup_f32 v80, v65, v64, 1.0
	s_cbranch_vccnz .LBB0_761
	v_pk_mul_f32 v[64:65], v[48:49], v[80:81] op_sel_hi:[1,0]
	v_pk_mul_f32 v[66:67], v[50:51], v[80:81] op_sel_hi:[1,0]
	v_add_u32_e32 v68, s53, v237
	ds_write_b128 v68, v[64:67]
	v_pk_mul_f32 v[64:65], v[52:53], v[80:81] op_sel_hi:[1,0]
	v_pk_mul_f32 v[66:67], v[54:55], v[80:81] op_sel_hi:[1,0]
	ds_write_b128 v68, v[64:67] offset:1024
	v_pk_mul_f32 v[64:65], v[56:57], v[80:81] op_sel_hi:[1,0]
	v_pk_mul_f32 v[66:67], v[58:59], v[80:81] op_sel_hi:[1,0]
	ds_write_b128 v68, v[64:67] offset:2048
	v_pk_mul_f32 v[64:65], v[60:61], v[80:81] op_sel_hi:[1,0]
	v_pk_mul_f32 v[66:67], v[62:63], v[80:81] op_sel_hi:[1,0]
	ds_write_b128 v68, v[64:67] offset:3072
	v_pk_mul_f32 v[64:65], v[32:33], v[80:81] op_sel_hi:[1,0]
	v_pk_mul_f32 v[66:67], v[34:35], v[80:81] op_sel_hi:[1,0]
	ds_write_b128 v68, v[64:67] offset:4096
	v_pk_mul_f32 v[64:65], v[36:37], v[80:81] op_sel_hi:[1,0]
	v_pk_mul_f32 v[66:67], v[38:39], v[80:81] op_sel_hi:[1,0]
	ds_write_b128 v68, v[64:67] offset:5120
	v_pk_mul_f32 v[64:65], v[40:41], v[80:81] op_sel_hi:[1,0]
	v_pk_mul_f32 v[66:67], v[42:43], v[80:81] op_sel_hi:[1,0]
	ds_write_b128 v68, v[64:67] offset:6144
	v_pk_mul_f32 v[64:65], v[44:45], v[80:81] op_sel_hi:[1,0]
	v_pk_mul_f32 v[66:67], v[46:47], v[80:81] op_sel_hi:[1,0]
	ds_write_b128 v68, v[64:67] offset:7168
	v_pk_mul_f32 v[64:65], v[16:17], v[80:81] op_sel_hi:[1,0]
	v_pk_mul_f32 v[66:67], v[18:19], v[80:81] op_sel_hi:[1,0]
	ds_write_b128 v68, v[64:67] offset:8192
	v_pk_mul_f32 v[64:65], v[20:21], v[80:81] op_sel_hi:[1,0]
	v_pk_mul_f32 v[66:67], v[22:23], v[80:81] op_sel_hi:[1,0]
	ds_write_b128 v68, v[64:67] offset:9216
	v_pk_mul_f32 v[64:65], v[24:25], v[80:81] op_sel_hi:[1,0]
	v_pk_mul_f32 v[66:67], v[26:27], v[80:81] op_sel_hi:[1,0]
	ds_write_b128 v68, v[64:67] offset:10240
	v_pk_mul_f32 v[64:65], v[28:29], v[80:81] op_sel_hi:[1,0]
	v_pk_mul_f32 v[66:67], v[30:31], v[80:81] op_sel_hi:[1,0]
	ds_write_b128 v68, v[64:67] offset:11264
	v_pk_mul_f32 v[64:65], v[0:1], v[80:81] op_sel_hi:[1,0]
	v_pk_mul_f32 v[66:67], v[2:3], v[80:81] op_sel_hi:[1,0]
	ds_write_b128 v68, v[64:67] offset:12288
	v_pk_mul_f32 v[64:65], v[4:5], v[80:81] op_sel_hi:[1,0]
	v_pk_mul_f32 v[66:67], v[6:7], v[80:81] op_sel_hi:[1,0]
	ds_write_b128 v68, v[64:67] offset:13312
	v_pk_mul_f32 v[64:65], v[8:9], v[80:81] op_sel_hi:[1,0]
	v_pk_mul_f32 v[66:67], v[10:11], v[80:81] op_sel_hi:[1,0]
	ds_write_b128 v68, v[64:67] offset:14336
	v_pk_mul_f32 v[64:65], v[12:13], v[80:81] op_sel_hi:[1,0]
	v_pk_mul_f32 v[66:67], v[14:15], v[80:81] op_sel_hi:[1,0]
	ds_write_b128 v68, v[64:67] offset:15360

.LBB0_2799:
	s_lshl_b32 s8, s56, 5
	s_add_i32 s8, s8, s55
	v_readlane_b32 s18, v254, 6
	s_or_b32 s8, s8, s54
	v_readlane_b32 s19, v254, 7
	s_and_b64 s[18:19], s[18:19], exec
	s_cselect_b32 s58, s8, s45
	s_ashr_i32 s18, s58, 6
	s_lshl_b32 s8, s58, 7
	s_ashr_i32 s19, s18, 31
	s_and_b32 s8, s8, 0x780
	s_lshl_b64 s[38:39], s[18:19], 20
	s_lshl_b64 s[40:41], s[18:19], 21
	s_add_u32 s17, s12, s40
	s_addc_u32 s18, s13, s41
	s_lshl_b32 s19, s58, 3
	s_and_b32 s57, s19, 0x180
	s_lshl_b32 s22, s57, 1
	s_add_u32 s17, s17, s22
	s_addc_u32 s19, s18, 0
	s_add_u32 s18, s17, s36
	s_addc_u32 s19, s19, s37
	s_add_u32 s17, s48, s40
	s_addc_u32 s21, s49, s41
	s_add_u32 s20, s17, s22
	s_addc_u32 s21, s21, 0
	s_add_u32 s17, s50, s40
	s_addc_u32 s23, s51, s41
	s_add_u32 s22, s17, s22
	s_addc_u32 s23, s23, 0
	v_lshl_add_u64 v[0:1], s[20:21], 0, v[216:217]
	v_lshl_add_u64 v[2:3], s[20:21], 0, v[220:221]
	v_lshl_add_u64 v[8:9], s[22:23], 0, v[216:217]
	v_lshl_add_u64 v[10:11], s[22:23], 0, v[220:221]
	v_lshl_add_u64 v[0:1], v[0:1], 0, v[218:219]
	v_lshl_add_u64 v[4:5], v[2:3], 0, v[222:223]
	v_lshl_add_u64 v[8:9], v[8:9], 0, v[218:219]
	v_lshl_add_u64 v[12:13], v[10:11], 0, v[222:223]
	global_load_dwordx4 v[0:3], v[0:1], off
	s_nop 0
	global_load_dwordx4 v[4:7], v[4:5], off
	s_nop 0
	global_load_dwordx4 v[8:11], v[8:9], off
	s_nop 0
	global_load_dwordx4 v[12:15], v[12:13], off
	v_or_b32_e32 v16, s8, v233
	v_lshlrev_b32_e32 v192, 10, v16
	v_lshl_add_u64 v[16:17], s[18:19], 0, v[192:193]
	v_mov_b32_e32 v215, v193
	v_lshl_add_u64 v[16:17], v[16:17], 0, v[214:215]
	global_load_dwordx4 v[160:163], v[16:17], off
	global_load_dwordx4 v[164:167], v[16:17], off offset:32
	global_load_dwordx4 v[168:171], v[16:17], off offset:64
	global_load_dwordx4 v[172:175], v[16:17], off offset:96
	v_lshl_add_u64 v[16:17], s[20:21], 0, v[196:197]
	v_lshl_add_u64 v[18:19], s[20:21], 0, v[198:199]
	v_lshl_add_u64 v[16:17], v[16:17], 0, v[218:219]
	v_lshl_add_u64 v[18:19], v[18:19], 0, v[222:223]
	global_load_dwordx4 v[176:179], v[16:17], off
	global_load_dwordx4 v[180:183], v[18:19], off
	v_add_u32_e32 v192, v202, v234
	v_add_u32_e32 v215, v204, v235
	v_add_u32_e32 v243, v206, v234
	v_add_u32_e32 v244, v208, v235
	s_mov_b32 s17, s16
	s_mov_b32 s18, s16
	s_mov_b32 s19, s16
	s_mov_b32 s20, s16
	s_mov_b32 s21, s16
	s_mov_b32 s22, s16
	s_mov_b32 s23, s16
	s_mov_b32 s24, s16
	s_mov_b32 s25, s16
	s_mov_b32 s26, s16
	s_mov_b32 s27, s16
	s_mov_b32 s28, s16
	s_mov_b32 s29, s16
	s_mov_b32 s30, s16
	s_mov_b32 s31, s16
	v_mov_b32_e32 v246, 0
	v_mov_b32_e32 v245, 0xf149f2ca
	s_waitcnt vmcnt(9)
	ds_write_b128 v192, v[0:3]
	s_waitcnt vmcnt(8)
	ds_write_b128 v215, v[4:7]
	s_waitcnt vmcnt(7)
	ds_write_b128 v243, v[8:11] offset:34816
	s_waitcnt vmcnt(6)
	ds_write_b128 v244, v[12:15] offset:34816
	s_waitcnt lgkmcnt(0)
	s_barrier
	ds_read_b128 v[0:3], v240
	ds_read_b128 v[4:7], v240 offset:32
	s_waitcnt vmcnt(5) lgkmcnt(1)
	v_mfma_f32_32x32x16_bf16 v[80:95], v[0:3], v[160:163], 0
	ds_read_b128 v[0:3], v240 offset:8704
	ds_read_b128 v[8:11], v240 offset:8736
	s_waitcnt lgkmcnt(1)
	v_mfma_f32_32x32x16_bf16 v[64:79], v[0:3], v[160:163], 0
	ds_read_b128 v[0:3], v240 offset:64
	s_waitcnt vmcnt(4)
	v_mfma_f32_32x32x16_bf16 v[80:95], v[4:7], v[164:167], v[80:95]
	ds_read_b128 v[4:7], v240 offset:8768
	ds_read_b128 v[16:19], v240 offset:96
	ds_read_b128 v[20:23], v240 offset:8800
	s_waitcnt vmcnt(1)
	ds_write_b128 v241, v[176:179] offset:17408
	s_waitcnt vmcnt(0)
	ds_write_b128 v242, v[180:183] offset:17408
	s_waitcnt lgkmcnt(0)
	s_barrier
	v_mfma_f32_32x32x16_bf16 v[64:79], v[8:11], v[164:167], v[64:79]
	v_mfma_f32_32x32x16_bf16 v[80:95], v[0:3], v[168:171], v[80:95]
	v_mfma_f32_32x32x16_bf16 v[64:79], v[4:7], v[168:171], v[64:79]
	v_mov_b64_e32 v[0:1], s[16:17]
	v_mov_b64_e32 v[2:3], s[18:19]
	v_mov_b64_e32 v[4:5], s[20:21]
	v_mov_b64_e32 v[6:7], s[22:23]
	v_mov_b64_e32 v[8:9], s[24:25]
	v_mov_b64_e32 v[10:11], s[26:27]
	v_mov_b64_e32 v[12:13], s[28:29]
	v_mfma_f32_32x32x16_bf16 v[80:95], v[16:19], v[172:175], v[80:95]
	v_mov_b64_e32 v[14:15], s[30:31]
	s_lshl_b32 s17, s58, 4
	s_and_b32 s17, s17, 0x300
	s_or_b32 s40, s40, s17
	v_mov_b64_e32 v[46:47], v[14:15]
	v_mov_b64_e32 v[62:63], v[14:15]
	v_lshl_add_u64 v[224:225], v[210:211], 0, s[40:41]
	v_mfma_f32_32x32x16_bf16 v[64:79], v[20:23], v[172:175], v[64:79]
	v_mov_b64_e32 v[30:31], v[14:15]
	v_lshl_add_u64 v[226:227], v[212:213], 0, s[40:41]
	s_mov_b64 s[18:19], 0
	v_mov_b64_e32 v[28:29], v[12:13]
	v_mov_b64_e32 v[26:27], v[10:11]
	v_mov_b64_e32 v[24:25], v[8:9]
	v_mov_b64_e32 v[22:23], v[6:7]
	v_mov_b64_e32 v[20:21], v[4:5]
	v_mov_b64_e32 v[18:19], v[2:3]
	v_mov_b64_e32 v[16:17], v[0:1]
	v_mov_b64_e32 v[44:45], v[12:13]
	v_mov_b64_e32 v[42:43], v[10:11]
	v_mov_b64_e32 v[40:41], v[8:9]
	v_mov_b64_e32 v[38:39], v[6:7]
	v_mov_b64_e32 v[36:37], v[4:5]
	v_mov_b64_e32 v[34:35], v[2:3]
	v_mov_b64_e32 v[32:33], v[0:1]
	v_mov_b64_e32 v[60:61], v[12:13]
	v_mov_b64_e32 v[58:59], v[10:11]
	v_mov_b64_e32 v[56:57], v[8:9]
	v_mov_b64_e32 v[54:55], v[6:7]
	v_mov_b64_e32 v[52:53], v[4:5]
	v_mov_b64_e32 v[50:51], v[2:3]
	v_mov_b64_e32 v[48:49], v[0:1]
	v_readfirstlane_b32 s98, v226
	v_readfirstlane_b32 s99, v227
	s_nop 3
	v_subrev_u32_e32 v247, s98, v226
	v_add_u32_e32 v252, 0x8000, v247
	v_add_u32_e32 v253, 0x10000, v247
	v_add_u32_e32 v245, 0x18000, v247
	s_add_u32 s100, s98, 0xbf10000
	s_addc_u32 s101, s99, 0
	s_add_u32 s98, s98, 0xaf20000
	s_addc_u32 s99, s99, 0
	s_mov_b32 s17, 0
	s_cmp_lg_u64 s[14:15], 0
	s_cbranch_scc0 .Lprio_skip_1
	s_setprio 1
